# LN0 row loop: the 8 modulation-vector loads of a row issued together ahead of the next-row prefetch; counted vmcnt keeps the prefetch in flight
# baseline (speedup 1.0000x reference)
.LBB0_157:
	s_or_b64 exec, exec, s[34:35]
	v_mov_b32_e32 v52, v28
	v_mov_b32_e32 v53, v24
	v_mov_b32_e32 v54, v29
	v_mov_b32_e32 v55, v25
	v_pk_add_f32 v[52:53], v[52:53], v[54:55]
	v_mov_b32_e32 v54, v30
	v_mov_b32_e32 v55, v26
	v_pk_add_f32 v[52:53], v[54:55], v[52:53]
	v_mov_b32_e32 v54, v31
	v_mov_b32_e32 v55, v27
	v_pk_add_f32 v[52:53], v[54:55], v[52:53]
	v_add_f32_e32 v32, 0, v52
	v_add_f32_e32 v51, v32, v53
	v_mov_b32_e32 v52, v20
	v_mov_b32_e32 v53, v16
	v_mov_b32_e32 v54, v21
	v_mov_b32_e32 v55, v17
	v_pk_add_f32 v[60:61], v[52:53], v[54:55]
	v_mov_b32_e32 v62, v22
	v_mov_b32_e32 v63, v18
	v_pk_add_f32 v[60:61], v[62:63], v[60:61]
	v_mov_b32_e32 v62, v23
	v_mov_b32_e32 v63, v19
	v_pk_add_f32 v[60:61], v[62:63], v[60:61]
	v_lshl_add_u64 v[34:35], v[34:35], 0, s[20:21]
	v_add_f32_e32 v32, v51, v60
	v_add_f32_e32 v32, v32, v61
	s_nop 1
	v_add_f32_dpp v32, v32, v32 quad_perm:[1,0,3,2] row_mask:0xf bank_mask:0xf bound_ctrl:1
	s_nop 1
	v_add_f32_dpp v32, v32, v32 quad_perm:[2,3,0,1] row_mask:0xf bank_mask:0xf bound_ctrl:1
	s_nop 1
	v_add_f32_dpp v32, v32, v32 row_half_mirror row_mask:0xf bank_mask:0xf bound_ctrl:1
	s_nop 1
	v_add_f32_dpp v32, v32, v32 row_mirror row_mask:0xf bank_mask:0xf bound_ctrl:1
	ds_bpermute_b32 v46, v47, v32
	s_waitcnt lgkmcnt(0)
	v_add_f32_e32 v32, v32, v46
	ds_bpermute_b32 v46, v49, v32
	s_waitcnt lgkmcnt(0)
	v_add_f32_e32 v32, v32, v46
	v_mul_f32_e32 v32, 0x3a800000, v32
	v_pk_add_f32 v[28:29], v[28:29], v[32:33] op_sel_hi:[1,0] neg_lo:[0,1] neg_hi:[0,1]
	v_pk_add_f32 v[24:25], v[24:25], v[32:33] op_sel_hi:[1,0] neg_lo:[0,1] neg_hi:[0,1]
	v_mov_b32_e32 v70, v29
	v_mov_b32_e32 v71, v25
	v_pk_add_f32 v[30:31], v[30:31], v[32:33] op_sel_hi:[1,0] neg_lo:[0,1] neg_hi:[0,1]
	v_pk_add_f32 v[26:27], v[26:27], v[32:33] op_sel_hi:[1,0] neg_lo:[0,1] neg_hi:[0,1]
	v_mov_b32_e32 v68, v28
	v_mov_b32_e32 v69, v24
	v_pk_mul_f32 v[70:71], v[70:71], v[70:71]
	v_mov_b32_e32 v60, v30
	v_mov_b32_e32 v61, v26
	v_pk_fma_f32 v[68:69], v[68:69], v[68:69], v[70:71]
	v_mov_b32_e32 v62, v31
	v_mov_b32_e32 v63, v27
	v_pk_fma_f32 v[60:61], v[60:61], v[60:61], v[68:69]
	v_pk_add_f32 v[68:69], v[20:21], v[32:33] op_sel_hi:[1,0] neg_lo:[0,1] neg_hi:[0,1]
	v_pk_add_f32 v[72:73], v[16:17], v[32:33] op_sel_hi:[1,0] neg_lo:[0,1] neg_hi:[0,1]
	v_pk_fma_f32 v[60:61], v[62:63], v[62:63], v[60:61]
	v_pk_add_f32 v[62:63], v[22:23], v[32:33] op_sel_hi:[1,0] neg_lo:[0,1] neg_hi:[0,1]
	v_mov_b32_e32 v22, v73
	v_mov_b32_e32 v23, v69
	v_pk_add_f32 v[70:71], v[18:19], v[32:33] op_sel_hi:[1,0] neg_lo:[0,1] neg_hi:[0,1]
	v_mov_b32_e32 v20, v72
	v_mov_b32_e32 v21, v68
	v_pk_mul_f32 v[22:23], v[22:23], v[22:23]
	v_mov_b32_e32 v16, v70
	v_mov_b32_e32 v17, v62
	v_pk_fma_f32 v[20:21], v[20:21], v[20:21], v[22:23]
	v_mov_b32_e32 v18, v71
	v_mov_b32_e32 v19, v63
	v_pk_fma_f32 v[16:17], v[16:17], v[16:17], v[20:21]
	v_mov_b32_e32 v46, v50
	v_pk_fma_f32 v[16:17], v[18:19], v[18:19], v[16:17]
	v_add_f32_e32 v18, v60, v61
	v_add_f32_e32 v17, v17, v18
	v_add_f32_e32 v16, v16, v17
	s_cmp_eq_u64 s[6:7], 0
	s_cbranch_scc1 .Lln0_w0
	s_waitcnt vmcnt(4)
	s_branch .Lln0_w1

.Lln0_w1:
	v_pk_add_f32 v[18:19], v[94:95], 1.0 op_sel_hi:[1,0]
	v_add_f32_dpp v16, v16, v16 quad_perm:[1,0,3,2] row_mask:0xf bank_mask:0xf bound_ctrl:1
	s_nop 1
	v_add_f32_dpp v16, v16, v16 quad_perm:[2,3,0,1] row_mask:0xf bank_mask:0xf bound_ctrl:1
	s_nop 1
	v_add_f32_dpp v16, v16, v16 row_half_mirror row_mask:0xf bank_mask:0xf bound_ctrl:1
	s_nop 1
	v_add_f32_dpp v16, v16, v16 row_mirror row_mask:0xf bank_mask:0xf bound_ctrl:1
	ds_bpermute_b32 v17, v47, v16
	s_waitcnt lgkmcnt(0)
	v_add_f32_e32 v16, v16, v17
	ds_bpermute_b32 v17, v49, v16
	s_waitcnt lgkmcnt(0)
	v_add_f32_e32 v16, v16, v17
	v_fmamk_f32 v16, v16, 0x3a800000, v48
	v_mul_f32_e32 v17, 0x4b800000, v16
	v_cmp_gt_f32_e64 s[6:7], s41, v16
	s_nop 1
	v_cndmask_b32_e64 v16, v16, v17, s[6:7]
	v_rsq_f32_e32 v20, v16
	v_pk_add_f32 v[16:17], v[92:93], 1.0 op_sel_hi:[1,0]
	v_mul_f32_e32 v21, 0x45800000, v20
	v_cndmask_b32_e64 v32, v20, v21, s[6:7]
	v_pk_mul_f32 v[20:21], v[28:29], v[32:33] op_sel_hi:[1,0]
	v_pk_mul_f32 v[24:25], v[24:25], v[32:33] op_sel_hi:[1,0]
	v_pk_fma_f32 v[16:17], v[16:17], v[20:21], v[88:89]
	v_pk_mul_f32 v[20:21], v[30:31], v[32:33] op_sel_hi:[1,0]
	v_cvt_pk_bf16_f32 v16, v16, v17
	v_pk_fma_f32 v[18:19], v[18:19], v[20:21], v[90:91]
	v_pk_mul_f32 v[26:27], v[26:27], v[32:33] op_sel_hi:[1,0]
	v_cvt_pk_bf16_f32 v17, v18, v19
	global_store_dwordx2 v[44:45], v[16:17], off
	v_pk_mul_f32 v[60:61], v[72:73], v[32:33] op_sel_hi:[1,0]
	s_and_b64 s[6:7], exec, vcc
	s_or_b64 s[26:27], s[6:7], s[26:27]
	v_pk_add_f32 v[16:17], v[96:97], 1.0 op_sel_hi:[1,0]
	v_pk_add_f32 v[18:19], v[98:99], 1.0 op_sel_hi:[1,0]
	v_pk_fma_f32 v[16:17], v[16:17], v[24:25], v[100:101]
	v_pk_fma_f32 v[18:19], v[18:19], v[26:27], v[102:103]
	v_cvt_pk_bf16_f32 v16, v16, v17
	v_cvt_pk_bf16_f32 v17, v18, v19
	global_store_dwordx2 v[44:45], v[16:17], off offset:512
	v_pk_mul_f32 v[26:27], v[68:69], v[32:33] op_sel_hi:[1,0]
	v_pk_mul_f32 v[28:29], v[62:63], v[32:33] op_sel_hi:[1,0]
	v_pk_mul_f32 v[62:63], v[70:71], v[32:33] op_sel_hi:[1,0]
	v_pk_add_f32 v[16:17], v[104:105], 1.0 op_sel_hi:[1,0]
	v_pk_add_f32 v[18:19], v[106:107], 1.0 op_sel_hi:[1,0]
	v_pk_fma_f32 v[16:17], v[26:27], v[16:17], v[108:109]
	v_pk_fma_f32 v[18:19], v[28:29], v[18:19], v[110:111]
	v_cvt_pk_bf16_f32 v16, v16, v17
	v_cvt_pk_bf16_f32 v17, v18, v19
	global_store_dwordx2 v[44:45], v[16:17], off offset:1024
	s_waitcnt vmcnt(3)
	v_mov_b64_e32 v[30:31], v[2:3]
	v_mov_b64_e32 v[26:27], v[6:7]
	v_mov_b64_e32 v[22:23], v[10:11]
	v_mov_b64_e32 v[18:19], v[14:15]
	v_mov_b64_e32 v[28:29], v[0:1]
	v_mov_b64_e32 v[24:25], v[4:5]
	v_mov_b64_e32 v[20:21], v[8:9]
	v_mov_b64_e32 v[16:17], v[12:13]
	v_pk_add_f32 v[52:53], v[112:113], 1.0 op_sel_hi:[1,0]
	v_pk_add_f32 v[54:55], v[114:115], 1.0 op_sel_hi:[1,0]
	v_pk_fma_f32 v[52:53], v[60:61], v[52:53], v[116:117]
	v_pk_fma_f32 v[54:55], v[62:63], v[54:55], v[118:119]
	v_cvt_pk_bf16_f32 v52, v52, v53
	v_cvt_pk_bf16_f32 v53, v54, v55
	global_store_dwordx2 v[44:45], v[52:53], off offset:1536
	v_lshl_add_u64 v[44:45], v[44:45], 0, s[30:31]
	s_andn2_b64 exec, exec, s[26:27]
	s_cbranch_execz .LBB0_160
.LBB0_158:
	v_add_u32_e32 v50, s20, v46
	v_cmp_lt_i32_e64 s[6:7], s40, v46
	v_add_u32_e32 v32, 0xffffe000, v46
	v_lshrrev_b32_e32 v32, 12, v32
	v_mad_u32_u24 v32, v32, s39, s39
	v_cndmask_b32_e64 v32, 0, v32, s[6:7]
	v_lshl_add_u64 v[52:53], v[32:33], 2, s[18:19]
	v_lshl_add_u64 v[64:65], v[52:53], 0, s[28:29]
	v_lshl_add_u64 v[66:67], v[52:53], 0, v[36:37]
	v_lshl_add_u64 v[68:69], v[64:65], 0, v[36:37]
	v_lshl_add_u64 v[56:57], v[64:65], 0, v[38:39]
	v_lshl_add_u64 v[84:85], v[64:65], 0, v[40:41]
	v_lshl_add_u64 v[86:87], v[64:65], 0, v[42:43]
	global_load_dwordx4 v[88:91], v[66:67], off
	global_load_dwordx4 v[92:95], v[68:69], off
	global_load_dwordx4 v[96:99], v[56:57], off
	global_load_dwordx4 v[100:103], v[66:67], off offset:1024
	global_load_dwordx4 v[104:107], v[84:85], off
	global_load_dwordx4 v[108:111], v[66:67], off offset:2048
	global_load_dwordx4 v[112:115], v[86:87], off
	global_load_dwordx4 v[116:119], v[66:67], off offset:3072
	v_cmp_gt_i32_e64 s[6:7], s36, v50
	v_cmp_lt_i32_e32 vcc, s38, v50
	s_and_saveexec_b64 s[34:35], s[6:7]
	s_cbranch_execz .LBB0_157
	v_add_u32_e32 v0, 0xffffe000, v50
	v_cmp_gt_i32_e64 s[6:7], s37, v50
	v_mov_b32_e32 v2, s11
	v_mov_b32_e32 v3, s9
	v_cndmask_b32_e64 v1, 0, v35, s[6:7]
	v_cndmask_b32_e64 v0, v0, v34, s[6:7]
	v_cndmask_b32_e64 v3, v2, v3, s[6:7]
	v_mov_b32_e32 v2, s10
	v_mov_b32_e32 v4, s8
	v_cndmask_b32_e64 v2, v2, v4, s[6:7]
	v_lshlrev_b64 v[0:1], 12, v[0:1]
	v_lshl_add_u64 v[0:1], v[2:3], 0, v[0:1]
	v_lshl_add_u64 v[52:53], v[0:1], 0, v[36:37]
	global_load_dwordx4 v[0:3], v[52:53], off
	global_load_dwordx4 v[4:7], v[52:53], off offset:1024
	global_load_dwordx4 v[8:11], v[52:53], off offset:2048
	global_load_dwordx4 v[12:15], v[52:53], off offset:3072
	s_branch .LBB0_157
